# phase-4 kv-up V^T tiles stored via wave-private LDS transpose (8 feature rows x 128 B per store instead of 16-byte scattered pieces)
# speedup vs baseline: 1.0137x; 1.0058x over previous
.Lp4kv_vt:
	s_nop 15
	v_lshlrev_b32_e32 v160, 1, v86
	v_lshl_add_u64 v[88:89], v[82:83], 0, v[160:161]
	s_nop 0
	v_readfirstlane_b32 s32, v88
	v_readfirstlane_b32 s33, v89
	v_readfirstlane_b32 s30, v186
	s_lshr_b32 s30, s30, 6
	s_mul_i32 s30, s30, 0x2400
	v_and_b32_e32 v90, 31, v186
	v_bfe_u32 v91, v186, 5, 1
	v_mul_u32_u24_e32 v90, 144, v90
	v_lshl_add_u32 v90, v91, 3, v90
	v_add_u32_e32 v90, s30, v90
	v_and_b32_e32 v92, 63, v186
	v_lshrrev_b32_e32 v93, 3, v92
	v_and_b32_e32 v92, 7, v92
	v_mul_u32_u24_e32 v94, 144, v93
	v_lshl_add_u32 v94, v92, 4, v94
	v_add_u32_e32 v94, s30, v94
	v_lshlrev_b32_e32 v95, 14, v93
	v_lshl_add_u32 v95, v92, 4, v95
	v_cvt_pk_bf16_f32 v96, v48, v49
	v_cvt_pk_bf16_f32 v97, v50, v51
	ds_write_b64 v90, v[96:97]
	v_cvt_pk_bf16_f32 v98, v52, v53
	v_cvt_pk_bf16_f32 v99, v54, v55
	ds_write_b64 v90, v[98:99] offset:16
	v_cvt_pk_bf16_f32 v100, v56, v57
	v_cvt_pk_bf16_f32 v101, v58, v59
	ds_write_b64 v90, v[100:101] offset:32
	v_cvt_pk_bf16_f32 v102, v60, v61
	v_cvt_pk_bf16_f32 v103, v62, v63
	ds_write_b64 v90, v[102:103] offset:48
	v_cvt_pk_bf16_f32 v104, v64, v65
	v_cvt_pk_bf16_f32 v105, v66, v67
	ds_write_b64 v90, v[104:105] offset:4608
	v_cvt_pk_bf16_f32 v106, v68, v69
	v_cvt_pk_bf16_f32 v107, v70, v71
	ds_write_b64 v90, v[106:107] offset:4624
	v_cvt_pk_bf16_f32 v108, v72, v73
	v_cvt_pk_bf16_f32 v109, v74, v75
	ds_write_b64 v90, v[108:109] offset:4640
	v_cvt_pk_bf16_f32 v110, v76, v77
	v_cvt_pk_bf16_f32 v111, v78, v79
	ds_write_b64 v90, v[110:111] offset:4656
	v_cvt_pk_bf16_f32 v112, v16, v17
	v_cvt_pk_bf16_f32 v113, v18, v19
	ds_write_b64 v90, v[112:113] offset:64
	v_cvt_pk_bf16_f32 v114, v20, v21
	v_cvt_pk_bf16_f32 v115, v22, v23
	ds_write_b64 v90, v[114:115] offset:80
	v_cvt_pk_bf16_f32 v116, v24, v25
	v_cvt_pk_bf16_f32 v117, v26, v27
	ds_write_b64 v90, v[116:117] offset:96
	v_cvt_pk_bf16_f32 v118, v28, v29
	v_cvt_pk_bf16_f32 v119, v30, v31
	ds_write_b64 v90, v[118:119] offset:112
	v_cvt_pk_bf16_f32 v120, v32, v33
	v_cvt_pk_bf16_f32 v121, v34, v35
	ds_write_b64 v90, v[120:121] offset:4672
	v_cvt_pk_bf16_f32 v122, v36, v37
	v_cvt_pk_bf16_f32 v123, v38, v39
	ds_write_b64 v90, v[122:123] offset:4688
	v_cvt_pk_bf16_f32 v124, v40, v41
	v_cvt_pk_bf16_f32 v125, v42, v43
	ds_write_b64 v90, v[124:125] offset:4704
	v_cvt_pk_bf16_f32 v126, v44, v45
	v_cvt_pk_bf16_f32 v127, v46, v47
	ds_write_b64 v90, v[126:127] offset:4720
	s_waitcnt lgkmcnt(0)
	ds_read_b128 v[96:99], v94
	ds_read_b128 v[100:103], v94 offset:1152
	ds_read_b128 v[104:107], v94 offset:2304
	ds_read_b128 v[108:111], v94 offset:3456
	ds_read_b128 v[112:115], v94 offset:4608
	ds_read_b128 v[116:119], v94 offset:5760
	ds_read_b128 v[120:123], v94 offset:6912
	ds_read_b128 v[124:127], v94 offset:8064
	s_waitcnt lgkmcnt(7)
	global_store_dwordx4 v95, v[96:99], s[32:33]
	s_add_u32 s32, s32, 0x20000
	s_addc_u32 s33, s33, 0
	s_waitcnt lgkmcnt(6)
	global_store_dwordx4 v95, v[100:103], s[32:33]
	s_add_u32 s32, s32, 0x20000
	s_addc_u32 s33, s33, 0
	s_waitcnt lgkmcnt(5)
	global_store_dwordx4 v95, v[104:107], s[32:33]
	s_add_u32 s32, s32, 0x20000
	s_addc_u32 s33, s33, 0
	s_waitcnt lgkmcnt(4)
	global_store_dwordx4 v95, v[108:111], s[32:33]
	s_add_u32 s32, s32, 0x20000
	s_addc_u32 s33, s33, 0
	s_waitcnt lgkmcnt(3)
	global_store_dwordx4 v95, v[112:115], s[32:33]
	s_add_u32 s32, s32, 0x20000
	s_addc_u32 s33, s33, 0
	s_waitcnt lgkmcnt(2)
	global_store_dwordx4 v95, v[116:119], s[32:33]
	s_add_u32 s32, s32, 0x20000
	s_addc_u32 s33, s33, 0
	s_waitcnt lgkmcnt(1)
	global_store_dwordx4 v95, v[120:123], s[32:33]
	s_add_u32 s32, s32, 0x20000
	s_addc_u32 s33, s33, 0
	s_waitcnt lgkmcnt(0)
	global_store_dwordx4 v95, v[124:127], s[32:33]
	s_mov_b64 s[6:7], -1
	s_movk_i32 s34, 0x3fff
